# kbar loads 32 in flight; P8 epilogue row-ssq loads hoisted (with store-data WAR pad); P3 list append: all atomics issued first then one wait
# baseline (speedup 1.0000x reference)
.LBB0_311:
	v_lshl_add_u64 v[14:15], v[8:9], 0, s[18:19]
	v_add_co_u32_e32 v16, vcc, 0x13000000, v14
	s_nop 1
	v_addc_co_u32_e32 v17, vcc, 0, v15, vcc
	global_load_dword v30, v[16:17], off
	global_load_dword v31, v[16:17], off offset:2048
	v_add_co_u32_e32 v16, vcc, 0x13001000, v14
	s_nop 1
	v_addc_co_u32_e32 v17, vcc, 0, v15, vcc
	global_load_dword v32, v[16:17], off
	global_load_dword v33, v[16:17], off offset:2048
	v_add_co_u32_e32 v16, vcc, 0x13002000, v14
	s_nop 1
	v_addc_co_u32_e32 v17, vcc, 0, v15, vcc
	global_load_dword v34, v[16:17], off
	global_load_dword v35, v[16:17], off offset:2048
	v_add_co_u32_e32 v16, vcc, 0x13003000, v14
	s_nop 1
	v_addc_co_u32_e32 v17, vcc, 0, v15, vcc
	global_load_dword v36, v[16:17], off
	global_load_dword v37, v[16:17], off offset:2048
	v_add_co_u32_e32 v16, vcc, 0x13004000, v14
	s_nop 1
	v_addc_co_u32_e32 v17, vcc, 0, v15, vcc
	global_load_dword v38, v[16:17], off
	global_load_dword v39, v[16:17], off offset:2048
	v_add_co_u32_e32 v16, vcc, 0x13005000, v14
	s_nop 1
	v_addc_co_u32_e32 v17, vcc, 0, v15, vcc
	global_load_dword v40, v[16:17], off
	global_load_dword v41, v[16:17], off offset:2048
	v_add_co_u32_e32 v16, vcc, 0x13006000, v14
	s_nop 1
	v_addc_co_u32_e32 v17, vcc, 0, v15, vcc
	global_load_dword v42, v[16:17], off
	global_load_dword v43, v[16:17], off offset:2048
	v_add_co_u32_e32 v16, vcc, 0x13007000, v14
	s_nop 1
	v_addc_co_u32_e32 v17, vcc, 0, v15, vcc
	global_load_dword v44, v[16:17], off
	global_load_dword v45, v[16:17], off offset:2048
	v_add_co_u32_e32 v16, vcc, 0x13008000, v14
	s_nop 1
	v_addc_co_u32_e32 v17, vcc, 0, v15, vcc
	global_load_dword v46, v[16:17], off
	global_load_dword v47, v[16:17], off offset:2048
	v_add_co_u32_e32 v16, vcc, 0x13009000, v14
	s_nop 1
	v_addc_co_u32_e32 v17, vcc, 0, v15, vcc
	global_load_dword v48, v[16:17], off
	global_load_dword v49, v[16:17], off offset:2048
	v_add_co_u32_e32 v16, vcc, 0x1300a000, v14
	s_nop 1
	v_addc_co_u32_e32 v17, vcc, 0, v15, vcc
	global_load_dword v50, v[16:17], off
	global_load_dword v51, v[16:17], off offset:2048
	v_add_co_u32_e32 v16, vcc, 0x1300b000, v14
	s_nop 1
	v_addc_co_u32_e32 v17, vcc, 0, v15, vcc
	global_load_dword v52, v[16:17], off
	global_load_dword v53, v[16:17], off offset:2048
	v_add_co_u32_e32 v16, vcc, 0x1300c000, v14
	s_nop 1
	v_addc_co_u32_e32 v17, vcc, 0, v15, vcc
	global_load_dword v54, v[16:17], off
	global_load_dword v55, v[16:17], off offset:2048
	v_add_co_u32_e32 v16, vcc, 0x1300d000, v14
	s_nop 1
	v_addc_co_u32_e32 v17, vcc, 0, v15, vcc
	global_load_dword v56, v[16:17], off
	global_load_dword v57, v[16:17], off offset:2048
	v_add_co_u32_e32 v16, vcc, 0x1300e000, v14
	s_nop 1
	v_addc_co_u32_e32 v17, vcc, 0, v15, vcc
	global_load_dword v58, v[16:17], off
	global_load_dword v59, v[16:17], off offset:2048
	v_add_co_u32_e32 v16, vcc, 0x1300f000, v14
	s_nop 1
	v_addc_co_u32_e32 v17, vcc, 0, v15, vcc
	global_load_dword v60, v[16:17], off
	global_load_dword v61, v[16:17], off offset:2048
	s_add_u32 s18, s18, 0x10000
	s_addc_u32 s19, s19, 0
	s_waitcnt vmcnt(0)
	v_lshlrev_b32_e32 v16, 16, v30
	v_and_b32_e32 v17, 0xffff0000, v30
	v_pk_add_f32 v[6:7], v[6:7], v[16:17]
	v_lshlrev_b32_e32 v16, 16, v31
	v_and_b32_e32 v17, 0xffff0000, v31
	v_pk_add_f32 v[6:7], v[6:7], v[16:17]
	v_lshlrev_b32_e32 v16, 16, v32
	v_and_b32_e32 v17, 0xffff0000, v32
	v_pk_add_f32 v[6:7], v[6:7], v[16:17]
	v_lshlrev_b32_e32 v16, 16, v33
	v_and_b32_e32 v17, 0xffff0000, v33
	v_pk_add_f32 v[6:7], v[6:7], v[16:17]
	v_lshlrev_b32_e32 v16, 16, v34
	v_and_b32_e32 v17, 0xffff0000, v34
	v_pk_add_f32 v[6:7], v[6:7], v[16:17]
	v_lshlrev_b32_e32 v16, 16, v35
	v_and_b32_e32 v17, 0xffff0000, v35
	v_pk_add_f32 v[6:7], v[6:7], v[16:17]
	v_lshlrev_b32_e32 v16, 16, v36
	v_and_b32_e32 v17, 0xffff0000, v36
	v_pk_add_f32 v[6:7], v[6:7], v[16:17]
	v_lshlrev_b32_e32 v16, 16, v37
	v_and_b32_e32 v17, 0xffff0000, v37
	v_pk_add_f32 v[6:7], v[6:7], v[16:17]
	v_lshlrev_b32_e32 v16, 16, v38
	v_and_b32_e32 v17, 0xffff0000, v38
	v_pk_add_f32 v[6:7], v[6:7], v[16:17]
	v_lshlrev_b32_e32 v16, 16, v39
	v_and_b32_e32 v17, 0xffff0000, v39
	v_pk_add_f32 v[6:7], v[6:7], v[16:17]
	v_lshlrev_b32_e32 v16, 16, v40
	v_and_b32_e32 v17, 0xffff0000, v40
	v_pk_add_f32 v[6:7], v[6:7], v[16:17]
	v_lshlrev_b32_e32 v16, 16, v41
	v_and_b32_e32 v17, 0xffff0000, v41
	v_pk_add_f32 v[6:7], v[6:7], v[16:17]
	v_lshlrev_b32_e32 v16, 16, v42
	v_and_b32_e32 v17, 0xffff0000, v42
	v_pk_add_f32 v[6:7], v[6:7], v[16:17]
	v_lshlrev_b32_e32 v16, 16, v43
	v_and_b32_e32 v17, 0xffff0000, v43
	v_pk_add_f32 v[6:7], v[6:7], v[16:17]
	v_lshlrev_b32_e32 v16, 16, v44
	v_and_b32_e32 v17, 0xffff0000, v44
	v_pk_add_f32 v[6:7], v[6:7], v[16:17]
	v_lshlrev_b32_e32 v16, 16, v45
	v_and_b32_e32 v17, 0xffff0000, v45
	v_pk_add_f32 v[6:7], v[6:7], v[16:17]
	v_lshlrev_b32_e32 v16, 16, v46
	v_and_b32_e32 v17, 0xffff0000, v46
	v_pk_add_f32 v[6:7], v[6:7], v[16:17]
	v_lshlrev_b32_e32 v16, 16, v47
	v_and_b32_e32 v17, 0xffff0000, v47
	v_pk_add_f32 v[6:7], v[6:7], v[16:17]
	v_lshlrev_b32_e32 v16, 16, v48
	v_and_b32_e32 v17, 0xffff0000, v48
	v_pk_add_f32 v[6:7], v[6:7], v[16:17]
	v_lshlrev_b32_e32 v16, 16, v49
	v_and_b32_e32 v17, 0xffff0000, v49
	v_pk_add_f32 v[6:7], v[6:7], v[16:17]
	v_lshlrev_b32_e32 v16, 16, v50
	v_and_b32_e32 v17, 0xffff0000, v50
	v_pk_add_f32 v[6:7], v[6:7], v[16:17]
	v_lshlrev_b32_e32 v16, 16, v51
	v_and_b32_e32 v17, 0xffff0000, v51
	v_pk_add_f32 v[6:7], v[6:7], v[16:17]
	v_lshlrev_b32_e32 v16, 16, v52
	v_and_b32_e32 v17, 0xffff0000, v52
	v_pk_add_f32 v[6:7], v[6:7], v[16:17]
	v_lshlrev_b32_e32 v16, 16, v53
	v_and_b32_e32 v17, 0xffff0000, v53
	v_pk_add_f32 v[6:7], v[6:7], v[16:17]
	v_lshlrev_b32_e32 v16, 16, v54
	v_and_b32_e32 v17, 0xffff0000, v54
	v_pk_add_f32 v[6:7], v[6:7], v[16:17]
	v_lshlrev_b32_e32 v16, 16, v55
	v_and_b32_e32 v17, 0xffff0000, v55
	v_pk_add_f32 v[6:7], v[6:7], v[16:17]
	v_lshlrev_b32_e32 v16, 16, v56
	v_and_b32_e32 v17, 0xffff0000, v56
	v_pk_add_f32 v[6:7], v[6:7], v[16:17]
	v_lshlrev_b32_e32 v16, 16, v57
	v_and_b32_e32 v17, 0xffff0000, v57
	v_pk_add_f32 v[6:7], v[6:7], v[16:17]
	v_lshlrev_b32_e32 v16, 16, v58
	v_and_b32_e32 v17, 0xffff0000, v58
	v_pk_add_f32 v[6:7], v[6:7], v[16:17]
	v_lshlrev_b32_e32 v16, 16, v59
	v_and_b32_e32 v17, 0xffff0000, v59
	v_pk_add_f32 v[6:7], v[6:7], v[16:17]
	v_lshlrev_b32_e32 v16, 16, v60
	v_and_b32_e32 v17, 0xffff0000, v60
	v_pk_add_f32 v[6:7], v[6:7], v[16:17]
	v_lshlrev_b32_e32 v16, 16, v61
	v_and_b32_e32 v17, 0xffff0000, v61
	v_pk_add_f32 v[6:7], v[6:7], v[16:17]
	s_cmp_eq_u32 s18, 0x40000
	s_cbranch_scc0 .LBB0_311
	s_and_saveexec_b64 s[18:19], s[0:1]
	ds_write_b64 v13, v[6:7]
	s_or_b64 exec, exec, s[18:19]
	s_waitcnt lgkmcnt(0)
	s_barrier
	s_and_saveexec_b64 s[18:19], s[4:5]
	s_cbranch_execz .LBB0_309
	ds_read_b64 v[8:9], v13
	s_lshl_b32 s24, s15, 8
	v_bitop3_b32 v14, s24, v0, v11 bitop3:0xc8
	v_lshl_or_b32 v14, s21, 9, v14
	v_and_or_b32 v14, s20, 63, v14
	v_ashrrev_i32_e32 v15, 31, v14
	s_waitcnt lgkmcnt(0)
	v_pk_add_f32 v[6:7], v[6:7], v[8:9]
	v_lshlrev_b64 v[8:9], 9, v[14:15]
	v_pk_mul_f32 v[6:7], v[6:7], s[10:11] op_sel_hi:[1,0]
	v_lshl_add_u64 v[8:9], v[2:3], 0, v[8:9]
	global_store_dwordx2 v[8:9], v[6:7], off
	s_branch .LBB0_309

.LBB0_647:
	s_or_b64 exec, exec, s[6:7]
	s_cmp_ge_u32 s73, s52
	s_waitcnt lgkmcnt(0)
	s_barrier
	s_cbranch_scc1 .LBB0_513
	ds_read_u8 v1, v85 offset:35328
	ds_read_u8 v2, v85 offset:35392
	ds_read_u8 v3, v85 offset:35456
	ds_read_u8 v4, v85 offset:35520
	ds_read_u8 v13, v85 offset:34880
	ds_read_u8 v14, v85 offset:34944
	ds_read_u8 v15, v85 offset:35008
	ds_read_u8 v16, v85 offset:35072
	ds_read_u8 v17, v85 offset:35136
	ds_read_u8 v18, v85 offset:35200
	ds_read_u8 v19, v85 offset:35264
	ds_read_u8 v20, v85 offset:34816
	v_add_u32_e32 v0, s22, v84
	v_add_u32_e32 v5, 64, v0
	v_add_u32_e32 v6, 0x80, v0
	v_add_u32_e32 v7, 0xc0, v0
	s_and_b32 s53, s98, 0xffffffc0
	v_or_b32_e32 v8, 0x4000, v0
	v_or_b32_e32 v9, 0x4000, v5
	v_or_b32_e32 v10, 0x4000, v6
	v_or_b32_e32 v11, 0x4000, v7
	v_or_b32_e32 v12, 0x8000, v0
	v_or_b32_e32 v21, 0x8000, v5
	v_or_b32_e32 v22, 0x8000, v6
	v_or_b32_e32 v23, 0x8000, v7
	s_mov_b32 s54, s73
	s_mov_b32 s100, s73
	s_mov_b32 s101, 0
	v_mov_b32_e32 v150, 0
	s_waitcnt lgkmcnt(0)
.Lp3_a1:
	s_and_b32 s6, s100, 0xff
	s_mov_b32 s10, 0
	v_cmp_eq_u16_sdwa s[40:41], v20, s6 src0_sel:BYTE_0 src1_sel:DWORD
	s_bcnt1_i32_b64 s7, s[40:41]
	s_add_i32 s10, s10, s7
	v_cmp_eq_u16_sdwa s[40:41], v13, s6 src0_sel:BYTE_0 src1_sel:DWORD
	s_bcnt1_i32_b64 s7, s[40:41]
	s_add_i32 s10, s10, s7
	v_cmp_eq_u16_sdwa s[40:41], v14, s6 src0_sel:BYTE_0 src1_sel:DWORD
	s_bcnt1_i32_b64 s7, s[40:41]
	s_add_i32 s10, s10, s7
	v_cmp_eq_u16_sdwa s[40:41], v15, s6 src0_sel:BYTE_0 src1_sel:DWORD
	s_bcnt1_i32_b64 s7, s[40:41]
	s_add_i32 s10, s10, s7
	v_cmp_eq_u16_sdwa s[40:41], v16, s6 src0_sel:BYTE_0 src1_sel:DWORD
	s_bcnt1_i32_b64 s7, s[40:41]
	s_add_i32 s10, s10, s7
	v_cmp_eq_u16_sdwa s[40:41], v17, s6 src0_sel:BYTE_0 src1_sel:DWORD
	s_bcnt1_i32_b64 s7, s[40:41]
	s_add_i32 s10, s10, s7
	v_cmp_eq_u16_sdwa s[40:41], v18, s6 src0_sel:BYTE_0 src1_sel:DWORD
	s_bcnt1_i32_b64 s7, s[40:41]
	s_add_i32 s10, s10, s7
	v_cmp_eq_u16_sdwa s[40:41], v19, s6 src0_sel:BYTE_0 src1_sel:DWORD
	s_bcnt1_i32_b64 s7, s[40:41]
	s_add_i32 s10, s10, s7
	v_cmp_eq_u16_sdwa s[40:41], v1, s6 src0_sel:BYTE_0 src1_sel:DWORD
	s_bcnt1_i32_b64 s7, s[40:41]
	s_add_i32 s10, s10, s7
	v_cmp_eq_u16_sdwa s[40:41], v2, s6 src0_sel:BYTE_0 src1_sel:DWORD
	s_bcnt1_i32_b64 s7, s[40:41]
	s_add_i32 s10, s10, s7
	v_cmp_eq_u16_sdwa s[40:41], v3, s6 src0_sel:BYTE_0 src1_sel:DWORD
	s_bcnt1_i32_b64 s7, s[40:41]
	s_add_i32 s10, s10, s7
	v_cmp_eq_u16_sdwa s[40:41], v4, s6 src0_sel:BYTE_0 src1_sel:DWORD
	s_bcnt1_i32_b64 s7, s[40:41]
	s_add_i32 s10, s10, s7
	s_cmp_eq_u32 s10, 0
	s_cbranch_scc1 .Lp3_a1n
	s_lshl_b64 s[40:41], 1, s101
	s_mov_b64 exec, s[40:41]
	s_add_i32 s42, s53, s100
	s_ashr_i32 s43, s42, 31
	s_lshl_b64 s[66:67], s[42:43], 2
	s_add_u32 s66, s25, s66
	s_addc_u32 s67, s24, s67
	v_mov_b32_e32 v151, s10
	global_atomic_add v150, v65, v151, s[66:67] sc0
	s_mov_b64 exec, -1
.Lp3_a1n:
	s_add_i32 s100, s100, 8
	s_add_i32 s101, s101, 1
	s_cmp_ge_u32 s100, s52
	s_cbranch_scc0 .Lp3_a1
	s_waitcnt vmcnt(0)
	s_mov_b32 s101, 0
	s_branch .LBB0_651

.LBB0_650:
	s_add_i32 s101, s101, 1
	s_add_i32 s54, s54, 8
	s_cmp_ge_u32 s54, s52
	s_cbranch_scc1 .LBB0_513
.LBB0_651:
	s_and_b32 s6, s54, 0xff
	s_waitcnt lgkmcnt(0)
	v_cmp_eq_u16_sdwa s[40:41], v20, s6 src0_sel:BYTE_0 src1_sel:DWORD
	v_cmp_eq_u16_sdwa s[38:39], v13, s6 src0_sel:BYTE_0 src1_sel:DWORD
	s_bcnt1_i32_b64 s65, s[40:41]
	s_bcnt1_i32_b64 s64, s[38:39]
	v_cmp_eq_u16_sdwa s[36:37], v14, s6 src0_sel:BYTE_0 src1_sel:DWORD
	s_add_i32 s7, s65, s64
	s_bcnt1_i32_b64 s63, s[36:37]
	v_cmp_eq_u16_sdwa s[34:35], v15, s6 src0_sel:BYTE_0 src1_sel:DWORD
	s_add_i32 s7, s7, s63
	s_bcnt1_i32_b64 s62, s[34:35]
	v_cmp_eq_u16_sdwa s[30:31], v16, s6 src0_sel:BYTE_0 src1_sel:DWORD
	s_add_i32 s7, s7, s62
	s_bcnt1_i32_b64 s61, s[30:31]
	v_cmp_eq_u16_sdwa s[28:29], v17, s6 src0_sel:BYTE_0 src1_sel:DWORD
	s_add_i32 s7, s7, s61
	s_bcnt1_i32_b64 s60, s[28:29]
	v_cmp_eq_u16_sdwa s[22:23], v18, s6 src0_sel:BYTE_0 src1_sel:DWORD
	s_add_i32 s7, s7, s60
	s_bcnt1_i32_b64 s59, s[22:23]
	v_cmp_eq_u16_sdwa s[20:21], v19, s6 src0_sel:BYTE_0 src1_sel:DWORD
	s_add_i32 s7, s7, s59
	s_bcnt1_i32_b64 s58, s[20:21]
	v_cmp_eq_u16_sdwa s[18:19], v1, s6 src0_sel:BYTE_0 src1_sel:DWORD
	s_add_i32 s7, s7, s58
	s_bcnt1_i32_b64 s57, s[18:19]
	v_cmp_eq_u16_sdwa s[16:17], v2, s6 src0_sel:BYTE_0 src1_sel:DWORD
	s_add_i32 s7, s7, s57
	s_bcnt1_i32_b64 s56, s[16:17]
	v_cmp_eq_u16_sdwa s[14:15], v3, s6 src0_sel:BYTE_0 src1_sel:DWORD
	s_add_i32 s7, s7, s56
	s_bcnt1_i32_b64 s55, s[14:15]
	s_add_i32 s10, s7, s55
	v_cmp_eq_u16_sdwa s[6:7], v4, s6 src0_sel:BYTE_0 src1_sel:DWORD
	s_bcnt1_i32_b64 s42, s[6:7]
	s_add_i32 s10, s10, s42
	s_cmp_eq_u32 s10, 0
	s_cbranch_scc1 .LBB0_650
	s_add_i32 s42, s53, s54
	s_ashr_i32 s43, s42, 31
	s_lshl_b64 s[42:43], s[42:43], 16
	s_add_u32 s44, s33, s42
	v_readlane_b32 s10, v150, s101
	s_addc_u32 s45, s50, s43
	s_and_saveexec_b64 s[42:43], s[40:41]
	s_cbranch_execnz .LBB0_668
	s_or_b64 exec, exec, s[42:43]
	s_add_i32 s10, s10, s65
	s_and_saveexec_b64 s[40:41], s[38:39]
	s_cbranch_execnz .LBB0_669

.LBB0_1289:
	v_lshl_add_u32 v148, s4, 8, v152
	v_ashrrev_i32_e32 v149, 31, v148
	v_lshl_add_u64 v[146:147], v[148:149], 2, s[8:9]
	global_load_dword v161, v[146:147], off
	global_load_dword v240, v[146:147], off offset:64
	global_load_dword v241, v[146:147], off offset:128
	global_load_dword v242, v[146:147], off offset:192
	global_load_dword v243, v[146:147], off offset:512
	global_load_dword v244, v[146:147], off offset:576
	global_load_dword v245, v[146:147], off offset:640
	global_load_dword v246, v[146:147], off offset:704
	v_lshl_or_b32 v144, s5, 8, v154
	v_ashrrev_i32_e32 v145, 31, v144
	v_lshl_add_u64 v[150:151], v[144:145], 1, s[10:11]
	v_or_b32_e32 v160, 16, v148
	s_waitcnt vmcnt(0)
	v_fmamk_f32 v144, v161, 0x3a000000, v158
	v_mul_f32_e32 v145, 0x4f800000, v144
	v_cmp_gt_f32_e32 vcc, s55, v144
	v_ashrrev_i32_e32 v161, 31, v160
	s_nop 0
	v_cndmask_b32_e32 v162, v144, v145, vcc
	v_sqrt_f32_e32 v163, v162
	v_lshlrev_b64 v[144:145], 10, v[148:149]
	v_lshl_add_u64 v[144:145], v[150:151], 0, v[144:145]
	v_add_u32_e32 v149, -1, v163
	v_add_u32_e32 v164, 1, v163
	v_fma_f32 v165, -v149, v163, v162
	v_fma_f32 v166, -v164, v163, v162
	v_cmp_ge_f32_e64 s[4:5], 0, v165
	s_nop 1
	v_cndmask_b32_e64 v149, v163, v149, s[4:5]
	v_cmp_lt_f32_e64 s[4:5], 0, v166
	s_nop 1
	v_cndmask_b32_e64 v149, v149, v164, s[4:5]
	v_mul_f32_e32 v163, 0x37800000, v149
	v_cndmask_b32_e32 v149, v149, v163, vcc
	v_cmp_class_f32_e32 vcc, v162, v159
	s_nop 1
	v_cndmask_b32_e32 v149, v149, v162, vcc
	v_div_scale_f32 v164, s[4:5], v149, v149, 1.0
	v_rcp_f32_e32 v165, v164
	v_div_scale_f32 v166, vcc, 1.0, v149, 1.0
	v_lshl_add_u64 v[162:163], v[160:161], 2, s[8:9]
	v_fma_f32 v167, -v164, v165, 1.0
	v_fmac_f32_e32 v165, v167, v165
	v_mul_f32_e32 v167, v166, v165
	v_fma_f32 v168, -v164, v167, v166
	v_fmac_f32_e32 v167, v168, v165
	v_fma_f32 v164, -v164, v167, v166
	v_div_fmas_f32 v164, v164, v165, v167
	v_div_fixup_f32 v164, v164, v149, 1.0
	v_pk_mul_f32 v[126:127], v[126:127], v[164:165] op_sel_hi:[1,0]
	v_pk_mul_f32 v[124:125], v[124:125], v[164:165] op_sel_hi:[1,0]
	v_pk_mul_f32 v[122:123], v[122:123], v[164:165] op_sel_hi:[1,0]
	v_pk_mul_f32 v[120:121], v[120:121], v[164:165] op_sel_hi:[1,0]
	v_pk_mul_f32 v[118:119], v[118:119], v[164:165] op_sel_hi:[1,0]
	v_pk_mul_f32 v[116:117], v[116:117], v[164:165] op_sel_hi:[1,0]
	v_pk_mul_f32 v[166:167], v[114:115], v[164:165] op_sel_hi:[1,0]
	v_pk_mul_f32 v[164:165], v[112:113], v[164:165] op_sel_hi:[1,0]
	v_cvt_pk_bf16_f32 v112, v124, v125
	v_cvt_pk_bf16_f32 v113, v126, v127
	v_cvt_pk_bf16_f32 v114, v120, v121
	v_cvt_pk_bf16_f32 v115, v122, v123
	global_store_dwordx4 v[144:145], v[112:115], off
	s_nop 1
	v_cvt_pk_bf16_f32 v112, v116, v117
	v_cvt_pk_bf16_f32 v113, v118, v119
	v_cvt_pk_bf16_f32 v114, v164, v165
	v_cvt_pk_bf16_f32 v115, v166, v167
	global_store_dwordx4 v[144:145], v[112:115], off offset:256
	s_nop 1
	v_mov_b32_e32 v113, v240
	s_nop 0
	v_or_b32_e32 v112, 32, v148
	v_fmamk_f32 v113, v113, 0x3a000000, v158
	v_mul_f32_e32 v114, 0x4f800000, v113
	v_cmp_gt_f32_e32 vcc, s55, v113
	s_nop 1
	v_cndmask_b32_e32 v118, v113, v114, vcc
	v_sqrt_f32_e32 v119, v118
	v_lshlrev_b64 v[114:115], 10, v[160:161]
	v_ashrrev_i32_e32 v113, 31, v112
	v_lshl_add_u64 v[114:115], v[150:151], 0, v[114:115]
	v_add_u32_e32 v120, -1, v119
	v_add_u32_e32 v121, 1, v119
	v_fma_f32 v122, -v120, v119, v118
	v_fma_f32 v123, -v121, v119, v118
	v_cmp_ge_f32_e64 s[4:5], 0, v122
	v_lshl_add_u64 v[116:117], v[112:113], 2, s[8:9]
	s_nop 0
	v_cndmask_b32_e64 v119, v119, v120, s[4:5]
	v_cmp_lt_f32_e64 s[4:5], 0, v123
	s_nop 1
	v_cndmask_b32_e64 v119, v119, v121, s[4:5]
	v_mul_f32_e32 v120, 0x37800000, v119
	v_cndmask_b32_e32 v119, v119, v120, vcc
	v_cmp_class_f32_e32 vcc, v118, v159
	s_nop 1
	v_cndmask_b32_e32 v118, v119, v118, vcc
	v_div_scale_f32 v119, s[4:5], v118, v118, 1.0
	v_rcp_f32_e32 v120, v119
	v_div_scale_f32 v121, vcc, 1.0, v118, 1.0
	v_fma_f32 v122, -v119, v120, 1.0
	v_fmac_f32_e32 v120, v122, v120
	v_mul_f32_e32 v122, v121, v120
	v_fma_f32 v123, -v119, v122, v121
	v_fmac_f32_e32 v122, v123, v120
	v_fma_f32 v119, -v119, v122, v121
	v_div_fmas_f32 v119, v119, v120, v122
	v_div_fixup_f32 v118, v119, v118, 1.0
	v_pk_mul_f32 v[110:111], v[110:111], v[118:119] op_sel_hi:[1,0]
	v_pk_mul_f32 v[108:109], v[108:109], v[118:119] op_sel_hi:[1,0]
	v_pk_mul_f32 v[106:107], v[106:107], v[118:119] op_sel_hi:[1,0]
	v_pk_mul_f32 v[104:105], v[104:105], v[118:119] op_sel_hi:[1,0]
	v_pk_mul_f32 v[102:103], v[102:103], v[118:119] op_sel_hi:[1,0]
	v_pk_mul_f32 v[100:101], v[100:101], v[118:119] op_sel_hi:[1,0]
	v_pk_mul_f32 v[120:121], v[98:99], v[118:119] op_sel_hi:[1,0]
	v_pk_mul_f32 v[118:119], v[96:97], v[118:119] op_sel_hi:[1,0]
	v_cvt_pk_bf16_f32 v96, v108, v109
	v_cvt_pk_bf16_f32 v97, v110, v111
	v_cvt_pk_bf16_f32 v98, v104, v105
	v_cvt_pk_bf16_f32 v99, v106, v107
	global_store_dwordx4 v[114:115], v[96:99], off
	s_nop 1
	v_cvt_pk_bf16_f32 v96, v100, v101
	v_cvt_pk_bf16_f32 v97, v102, v103
	v_cvt_pk_bf16_f32 v98, v118, v119
	v_cvt_pk_bf16_f32 v99, v120, v121
	global_store_dwordx4 v[114:115], v[96:99], off offset:256
	s_nop 1
	v_mov_b32_e32 v97, v241
	s_nop 0
	v_or_b32_e32 v96, 48, v148
	v_fmamk_f32 v97, v97, 0x3a000000, v158
	v_mul_f32_e32 v98, 0x4f800000, v97
	v_cmp_gt_f32_e32 vcc, s55, v97
	s_nop 1
	v_cndmask_b32_e32 v102, v97, v98, vcc
	v_sqrt_f32_e32 v103, v102
	v_lshlrev_b64 v[98:99], 10, v[112:113]
	v_ashrrev_i32_e32 v97, 31, v96
	v_lshl_add_u64 v[98:99], v[150:151], 0, v[98:99]
	v_add_u32_e32 v104, -1, v103
	v_add_u32_e32 v105, 1, v103
	v_fma_f32 v106, -v104, v103, v102
	v_fma_f32 v107, -v105, v103, v102
	v_cmp_ge_f32_e64 s[4:5], 0, v106
	v_lshl_add_u64 v[100:101], v[96:97], 2, s[8:9]
	s_nop 0
	v_cndmask_b32_e64 v103, v103, v104, s[4:5]
	v_cmp_lt_f32_e64 s[4:5], 0, v107
	s_nop 1
	v_cndmask_b32_e64 v103, v103, v105, s[4:5]
	v_mul_f32_e32 v104, 0x37800000, v103
	v_cndmask_b32_e32 v103, v103, v104, vcc
	v_cmp_class_f32_e32 vcc, v102, v159
	s_nop 1
	v_cndmask_b32_e32 v102, v103, v102, vcc
	v_div_scale_f32 v103, s[4:5], v102, v102, 1.0
	v_rcp_f32_e32 v104, v103
	v_div_scale_f32 v105, vcc, 1.0, v102, 1.0
	v_fma_f32 v106, -v103, v104, 1.0
	v_fmac_f32_e32 v104, v106, v104
	v_mul_f32_e32 v106, v105, v104
	v_fma_f32 v107, -v103, v106, v105
	v_fmac_f32_e32 v106, v107, v104
	v_fma_f32 v103, -v103, v106, v105
	v_div_fmas_f32 v103, v103, v104, v106
	v_div_fixup_f32 v102, v103, v102, 1.0
	v_pk_mul_f32 v[94:95], v[94:95], v[102:103] op_sel_hi:[1,0]
	v_pk_mul_f32 v[92:93], v[92:93], v[102:103] op_sel_hi:[1,0]
	v_pk_mul_f32 v[90:91], v[90:91], v[102:103] op_sel_hi:[1,0]
	v_pk_mul_f32 v[88:89], v[88:89], v[102:103] op_sel_hi:[1,0]
	v_pk_mul_f32 v[86:87], v[86:87], v[102:103] op_sel_hi:[1,0]
	v_pk_mul_f32 v[84:85], v[84:85], v[102:103] op_sel_hi:[1,0]
	v_pk_mul_f32 v[104:105], v[82:83], v[102:103] op_sel_hi:[1,0]
	v_pk_mul_f32 v[102:103], v[80:81], v[102:103] op_sel_hi:[1,0]
	v_cvt_pk_bf16_f32 v80, v92, v93
	v_cvt_pk_bf16_f32 v81, v94, v95
	v_cvt_pk_bf16_f32 v82, v88, v89
	v_cvt_pk_bf16_f32 v83, v90, v91
	global_store_dwordx4 v[98:99], v[80:83], off
	s_nop 1
	v_cvt_pk_bf16_f32 v80, v84, v85
	v_cvt_pk_bf16_f32 v81, v86, v87
	v_cvt_pk_bf16_f32 v82, v102, v103
	v_cvt_pk_bf16_f32 v83, v104, v105
	global_store_dwordx4 v[98:99], v[80:83], off offset:256
	s_nop 1
	v_mov_b32_e32 v80, v242
	v_fmamk_f32 v80, v80, 0x3a000000, v158
	v_mul_f32_e32 v81, 0x4f800000, v80
	v_cmp_gt_f32_e32 vcc, s55, v80
	s_nop 1
	v_cndmask_b32_e32 v82, v80, v81, vcc
	v_sqrt_f32_e32 v83, v82
	v_lshlrev_b64 v[80:81], 10, v[96:97]
	v_lshl_add_u64 v[80:81], v[150:151], 0, v[80:81]
	v_add_u32_e32 v84, -1, v83
	v_add_u32_e32 v85, 1, v83
	v_fma_f32 v86, -v84, v83, v82
	v_fma_f32 v87, -v85, v83, v82
	v_cmp_ge_f32_e64 s[4:5], 0, v86
	s_nop 1
	v_cndmask_b32_e64 v83, v83, v84, s[4:5]
	v_cmp_lt_f32_e64 s[4:5], 0, v87
	s_nop 1
	v_cndmask_b32_e64 v83, v83, v85, s[4:5]
	v_mul_f32_e32 v84, 0x37800000, v83
	v_cndmask_b32_e32 v83, v83, v84, vcc
	v_cmp_class_f32_e32 vcc, v82, v159
	s_nop 1
	v_cndmask_b32_e32 v82, v83, v82, vcc
	v_div_scale_f32 v83, s[4:5], v82, v82, 1.0
	v_rcp_f32_e32 v84, v83
	v_div_scale_f32 v85, vcc, 1.0, v82, 1.0
	v_fma_f32 v86, -v83, v84, 1.0
	v_fmac_f32_e32 v84, v86, v84
	v_mul_f32_e32 v86, v85, v84
	v_fma_f32 v87, -v83, v86, v85
	v_fmac_f32_e32 v86, v87, v84
	v_fma_f32 v83, -v83, v86, v85
	v_div_fmas_f32 v83, v83, v84, v86
	v_div_fixup_f32 v82, v83, v82, 1.0
	v_pk_mul_f32 v[78:79], v[78:79], v[82:83] op_sel_hi:[1,0]
	v_pk_mul_f32 v[76:77], v[76:77], v[82:83] op_sel_hi:[1,0]
	v_pk_mul_f32 v[74:75], v[74:75], v[82:83] op_sel_hi:[1,0]
	v_pk_mul_f32 v[72:73], v[72:73], v[82:83] op_sel_hi:[1,0]
	v_pk_mul_f32 v[70:71], v[70:71], v[82:83] op_sel_hi:[1,0]
	v_pk_mul_f32 v[68:69], v[68:69], v[82:83] op_sel_hi:[1,0]
	v_pk_mul_f32 v[84:85], v[66:67], v[82:83] op_sel_hi:[1,0]
	v_pk_mul_f32 v[82:83], v[64:65], v[82:83] op_sel_hi:[1,0]
	v_cvt_pk_bf16_f32 v64, v76, v77
	v_cvt_pk_bf16_f32 v65, v78, v79
	v_cvt_pk_bf16_f32 v66, v72, v73
	v_cvt_pk_bf16_f32 v67, v74, v75
	global_store_dwordx4 v[80:81], v[64:67], off
	s_nop 1
	v_cvt_pk_bf16_f32 v64, v68, v69
	v_cvt_pk_bf16_f32 v65, v70, v71
	v_cvt_pk_bf16_f32 v66, v82, v83
	v_cvt_pk_bf16_f32 v67, v84, v85
	global_store_dwordx4 v[80:81], v[64:67], off offset:256
	s_nop 1
	v_mov_b32_e32 v64, v243
	v_fmamk_f32 v64, v64, 0x3a000000, v158
	v_mul_f32_e32 v65, 0x4f800000, v64
	v_cmp_gt_f32_e32 vcc, s55, v64
	s_nop 1
	v_cndmask_b32_e32 v66, v64, v65, vcc
	v_sqrt_f32_e32 v67, v66
	v_lshl_add_u64 v[64:65], v[144:145], 0, s[16:17]
	v_add_u32_e32 v68, -1, v67
	v_add_u32_e32 v69, 1, v67
	v_fma_f32 v70, -v68, v67, v66
	v_fma_f32 v71, -v69, v67, v66
	v_cmp_ge_f32_e64 s[4:5], 0, v70
	s_nop 1
	v_cndmask_b32_e64 v67, v67, v68, s[4:5]
	v_cmp_lt_f32_e64 s[4:5], 0, v71
	s_nop 1
	v_cndmask_b32_e64 v67, v67, v69, s[4:5]
	v_mul_f32_e32 v68, 0x37800000, v67
	v_cndmask_b32_e32 v67, v67, v68, vcc
	v_cmp_class_f32_e32 vcc, v66, v159
	s_nop 1
	v_cndmask_b32_e32 v68, v67, v66, vcc
	v_div_scale_f32 v69, s[4:5], v68, v68, 1.0
	v_rcp_f32_e32 v70, v69
	v_add_co_u32_e32 v66, vcc, s56, v144
	v_fma_f32 v72, -v69, v70, 1.0
	s_nop 0
	v_addc_co_u32_e32 v67, vcc, 0, v145, vcc
	v_div_scale_f32 v71, vcc, 1.0, v68, 1.0
	v_fmac_f32_e32 v70, v72, v70
	v_mul_f32_e32 v72, v71, v70
	v_fma_f32 v73, -v69, v72, v71
	v_fmac_f32_e32 v72, v73, v70
	v_fma_f32 v69, -v69, v72, v71
	v_div_fmas_f32 v69, v69, v70, v72
	v_div_fixup_f32 v68, v69, v68, 1.0
	v_pk_mul_f32 v[62:63], v[62:63], v[68:69] op_sel_hi:[1,0]
	v_pk_mul_f32 v[60:61], v[60:61], v[68:69] op_sel_hi:[1,0]
	v_pk_mul_f32 v[58:59], v[58:59], v[68:69] op_sel_hi:[1,0]
	v_pk_mul_f32 v[56:57], v[56:57], v[68:69] op_sel_hi:[1,0]
	v_pk_mul_f32 v[54:55], v[54:55], v[68:69] op_sel_hi:[1,0]
	v_pk_mul_f32 v[52:53], v[52:53], v[68:69] op_sel_hi:[1,0]
	v_pk_mul_f32 v[70:71], v[50:51], v[68:69] op_sel_hi:[1,0]
	v_pk_mul_f32 v[68:69], v[48:49], v[68:69] op_sel_hi:[1,0]
	v_cvt_pk_bf16_f32 v48, v60, v61
	v_cvt_pk_bf16_f32 v49, v62, v63
	v_cvt_pk_bf16_f32 v50, v56, v57
	v_cvt_pk_bf16_f32 v51, v58, v59
	global_store_dwordx4 v[66:67], v[48:51], off
	s_nop 1
	v_cvt_pk_bf16_f32 v48, v52, v53
	v_cvt_pk_bf16_f32 v49, v54, v55
	v_cvt_pk_bf16_f32 v50, v68, v69
	v_cvt_pk_bf16_f32 v51, v70, v71
	global_store_dwordx4 v[64:65], v[48:51], off offset:256
	s_nop 1
	v_mov_b32_e32 v48, v244
	v_fmamk_f32 v48, v48, 0x3a000000, v158
	v_mul_f32_e32 v49, 0x4f800000, v48
	v_cmp_gt_f32_e32 vcc, s55, v48
	s_nop 1
	v_cndmask_b32_e32 v50, v48, v49, vcc
	v_sqrt_f32_e32 v51, v50
	v_lshl_add_u64 v[48:49], v[144:145], 0, s[18:19]
	v_add_u32_e32 v52, -1, v51
	v_add_u32_e32 v53, 1, v51
	v_fma_f32 v54, -v52, v51, v50
	v_fma_f32 v55, -v53, v51, v50
	v_cmp_ge_f32_e64 s[4:5], 0, v54
	s_nop 1
	v_cndmask_b32_e64 v51, v51, v52, s[4:5]
	v_cmp_lt_f32_e64 s[4:5], 0, v55
	s_nop 1
	v_cndmask_b32_e64 v51, v51, v53, s[4:5]
	v_mul_f32_e32 v52, 0x37800000, v51
	v_cndmask_b32_e32 v51, v51, v52, vcc
	v_cmp_class_f32_e32 vcc, v50, v159
	s_nop 1
	v_cndmask_b32_e32 v52, v51, v50, vcc
	v_div_scale_f32 v53, s[4:5], v52, v52, 1.0
	v_rcp_f32_e32 v54, v53
	v_add_co_u32_e32 v50, vcc, s57, v144
	v_fma_f32 v56, -v53, v54, 1.0
	s_nop 0
	v_addc_co_u32_e32 v51, vcc, 0, v145, vcc
	v_div_scale_f32 v55, vcc, 1.0, v52, 1.0
	v_fmac_f32_e32 v54, v56, v54
	v_mul_f32_e32 v56, v55, v54
	v_fma_f32 v57, -v53, v56, v55
	v_fmac_f32_e32 v56, v57, v54
	v_fma_f32 v53, -v53, v56, v55
	v_div_fmas_f32 v53, v53, v54, v56
	v_div_fixup_f32 v52, v53, v52, 1.0
	v_pk_mul_f32 v[46:47], v[46:47], v[52:53] op_sel_hi:[1,0]
	v_pk_mul_f32 v[44:45], v[44:45], v[52:53] op_sel_hi:[1,0]
	v_pk_mul_f32 v[42:43], v[42:43], v[52:53] op_sel_hi:[1,0]
	v_pk_mul_f32 v[40:41], v[40:41], v[52:53] op_sel_hi:[1,0]
	v_pk_mul_f32 v[38:39], v[38:39], v[52:53] op_sel_hi:[1,0]
	v_pk_mul_f32 v[36:37], v[36:37], v[52:53] op_sel_hi:[1,0]
	v_pk_mul_f32 v[54:55], v[34:35], v[52:53] op_sel_hi:[1,0]
	v_pk_mul_f32 v[52:53], v[32:33], v[52:53] op_sel_hi:[1,0]
	v_cvt_pk_bf16_f32 v32, v44, v45
	v_cvt_pk_bf16_f32 v33, v46, v47
	v_cvt_pk_bf16_f32 v34, v40, v41
	v_cvt_pk_bf16_f32 v35, v42, v43
	global_store_dwordx4 v[50:51], v[32:35], off
	s_nop 1
	v_cvt_pk_bf16_f32 v32, v36, v37
	v_cvt_pk_bf16_f32 v33, v38, v39
	v_cvt_pk_bf16_f32 v34, v52, v53
	v_cvt_pk_bf16_f32 v35, v54, v55
	global_store_dwordx4 v[48:49], v[32:35], off offset:256
	s_nop 1
	v_mov_b32_e32 v32, v245
	v_fmamk_f32 v32, v32, 0x3a000000, v158
	v_mul_f32_e32 v33, 0x4f800000, v32
	v_cmp_gt_f32_e32 vcc, s55, v32
	s_nop 1
	v_cndmask_b32_e32 v34, v32, v33, vcc
	v_sqrt_f32_e32 v35, v34
	v_lshl_add_u64 v[32:33], v[144:145], 0, s[20:21]
	v_add_u32_e32 v36, -1, v35
	v_add_u32_e32 v37, 1, v35
	v_fma_f32 v38, -v36, v35, v34
	v_fma_f32 v39, -v37, v35, v34
	v_cmp_ge_f32_e64 s[4:5], 0, v38
	s_nop 1
	v_cndmask_b32_e64 v35, v35, v36, s[4:5]
	v_cmp_lt_f32_e64 s[4:5], 0, v39
	s_nop 1
	v_cndmask_b32_e64 v35, v35, v37, s[4:5]
	v_mul_f32_e32 v36, 0x37800000, v35
	v_cndmask_b32_e32 v35, v35, v36, vcc
	v_cmp_class_f32_e32 vcc, v34, v159
	s_nop 1
	v_cndmask_b32_e32 v36, v35, v34, vcc
	v_div_scale_f32 v37, s[4:5], v36, v36, 1.0
	v_rcp_f32_e32 v38, v37
	v_add_co_u32_e32 v34, vcc, s58, v144
	v_fma_f32 v40, -v37, v38, 1.0
	s_nop 0
	v_addc_co_u32_e32 v35, vcc, 0, v145, vcc
	v_div_scale_f32 v39, vcc, 1.0, v36, 1.0
	v_fmac_f32_e32 v38, v40, v38
	v_mul_f32_e32 v40, v39, v38
	v_fma_f32 v41, -v37, v40, v39
	v_fmac_f32_e32 v40, v41, v38
	v_fma_f32 v37, -v37, v40, v39
	v_div_fmas_f32 v37, v37, v38, v40
	v_div_fixup_f32 v36, v37, v36, 1.0
	v_pk_mul_f32 v[30:31], v[30:31], v[36:37] op_sel_hi:[1,0]
	v_pk_mul_f32 v[28:29], v[28:29], v[36:37] op_sel_hi:[1,0]
	v_pk_mul_f32 v[26:27], v[26:27], v[36:37] op_sel_hi:[1,0]
	v_pk_mul_f32 v[24:25], v[24:25], v[36:37] op_sel_hi:[1,0]
	v_pk_mul_f32 v[22:23], v[22:23], v[36:37] op_sel_hi:[1,0]
	v_pk_mul_f32 v[20:21], v[20:21], v[36:37] op_sel_hi:[1,0]
	v_pk_mul_f32 v[38:39], v[18:19], v[36:37] op_sel_hi:[1,0]
	v_pk_mul_f32 v[36:37], v[16:17], v[36:37] op_sel_hi:[1,0]
	v_cvt_pk_bf16_f32 v16, v28, v29
	v_cvt_pk_bf16_f32 v17, v30, v31
	v_cvt_pk_bf16_f32 v18, v24, v25
	v_cvt_pk_bf16_f32 v19, v26, v27
	global_store_dwordx4 v[34:35], v[16:19], off
	s_nop 1
	v_cvt_pk_bf16_f32 v16, v20, v21
	v_cvt_pk_bf16_f32 v17, v22, v23
	v_cvt_pk_bf16_f32 v18, v36, v37
	v_cvt_pk_bf16_f32 v19, v38, v39
	global_store_dwordx4 v[32:33], v[16:19], off offset:256
	s_nop 1
	v_mov_b32_e32 v16, v246
	v_fmamk_f32 v16, v16, 0x3a000000, v158
	v_mul_f32_e32 v17, 0x4f800000, v16
	v_cmp_gt_f32_e32 vcc, s55, v16
	s_nop 1
	v_cndmask_b32_e32 v18, v16, v17, vcc
	v_sqrt_f32_e32 v19, v18
	v_lshl_add_u64 v[16:17], v[144:145], 0, s[22:23]
	v_add_u32_e32 v20, -1, v19
	v_add_u32_e32 v21, 1, v19
	v_fma_f32 v22, -v20, v19, v18
	v_fma_f32 v23, -v21, v19, v18
	v_cmp_ge_f32_e64 s[4:5], 0, v22
	s_nop 1
	v_cndmask_b32_e64 v19, v19, v20, s[4:5]
	v_cmp_lt_f32_e64 s[4:5], 0, v23
	s_nop 1
	v_cndmask_b32_e64 v19, v19, v21, s[4:5]
	v_mul_f32_e32 v20, 0x37800000, v19
	v_cndmask_b32_e32 v19, v19, v20, vcc
	v_cmp_class_f32_e32 vcc, v18, v159
	s_nop 1
	v_cndmask_b32_e32 v20, v19, v18, vcc
	v_div_scale_f32 v21, s[4:5], v20, v20, 1.0
	v_rcp_f32_e32 v22, v21
	v_add_co_u32_e32 v18, vcc, s59, v144
	v_fma_f32 v24, -v21, v22, 1.0
	s_nop 0
	v_addc_co_u32_e32 v19, vcc, 0, v145, vcc
	v_div_scale_f32 v23, vcc, 1.0, v20, 1.0
	v_fmac_f32_e32 v22, v24, v22
	v_mul_f32_e32 v24, v23, v22
	v_fma_f32 v25, -v21, v24, v23
	v_fmac_f32_e32 v24, v25, v22
	v_fma_f32 v21, -v21, v24, v23
	v_div_fmas_f32 v21, v21, v22, v24
	v_div_fixup_f32 v20, v21, v20, 1.0
	s_andn2_b64 vcc, exec, s[0:1]
	v_pk_mul_f32 v[14:15], v[14:15], v[20:21] op_sel_hi:[1,0]
	v_pk_mul_f32 v[12:13], v[12:13], v[20:21] op_sel_hi:[1,0]
	v_pk_mul_f32 v[10:11], v[10:11], v[20:21] op_sel_hi:[1,0]
	v_pk_mul_f32 v[8:9], v[8:9], v[20:21] op_sel_hi:[1,0]
	v_pk_mul_f32 v[6:7], v[6:7], v[20:21] op_sel_hi:[1,0]
	v_pk_mul_f32 v[4:5], v[4:5], v[20:21] op_sel_hi:[1,0]
	v_pk_mul_f32 v[22:23], v[2:3], v[20:21] op_sel_hi:[1,0]
	v_pk_mul_f32 v[20:21], v[0:1], v[20:21] op_sel_hi:[1,0]
	v_cvt_pk_bf16_f32 v0, v12, v13
	v_cvt_pk_bf16_f32 v1, v14, v15
	v_cvt_pk_bf16_f32 v2, v8, v9
	v_cvt_pk_bf16_f32 v3, v10, v11
	s_mov_b64 s[0:1], -1
	global_store_dwordx4 v[18:19], v[0:3], off
	s_nop 1
	v_cvt_pk_bf16_f32 v0, v4, v5
	v_cvt_pk_bf16_f32 v1, v6, v7
	v_cvt_pk_bf16_f32 v2, v20, v21
	v_cvt_pk_bf16_f32 v3, v22, v23
	global_store_dwordx4 v[16:17], v[0:3], off offset:256
	s_cbranch_vccnz .LBB0_1278
	s_andn2_b64 vcc, exec, s[6:7]
	s_cbranch_vccnz .LBB0_1277
	s_barrier
	s_branch .LBB0_1277
